# baseline (speedup 1.0000x reference)
; __device__ __forceinline__ void attn_phase(LAS unsigned char* lds, bf16_t* Qb, const bf16_t* KVb, const bf16_t* GZ, const float* sinkp) {
;     ...
;                     float mx = __builtin_fmaxf(s0[0], s1[0]);
; #pragma unroll
;                     for (int r = 1; r < 16; ++r) { float t_; asm("v_max3_f32 %0, %1, %2, %3" : "=v"(t_) : "v"(mx), "v"(s0[r]), "v"(s1[r])); mx = t_; }
;                     mx = fmaxf(mx, __shfl_xor(mx, 32));
;                     const float mx2 = mx * SC;
;                     const bool bump = mx2 > m_run + 8.f;
;                     if (__any(bump)) {
;                         const float m_new = bump ? mx2 : m_run, alpha = __builtin_amdgcn_exp2f(m_run - m_new);
;                         m_run = m_new; l_run *= alpha;
; #pragma unroll
;                         for (int dt = 0; dt < 4; ++dt)
; #pragma unroll
;                             for (int r = 0; r < 16; ++r) o[dt][r] *= alpha;
;                     }
.LBB0_176:
	v_add_u32_e32 v220, s3, v161
	v_add_u32_e32 v221, s3, v162
	v_add_u32_e32 v202, s3, v163
	v_add_u32_e32 v203, s3, v164
	v_add_u32_e32 v204, s3, v165
	v_add_u32_e32 v205, s3, v166
	v_add_u32_e32 v206, s3, v167
	v_add_u32_e32 v207, s3, v168
	ds_read_b64_tr_b16 v[208:209], v220 offset:16384
	ds_read_b64_tr_b16 v[210:211], v221 offset:16384
	ds_read_b64_tr_b16 v[212:213], v202 offset:16384
	ds_read_b64_tr_b16 v[214:215], v203 offset:16384
	ds_read_b64_tr_b16 v[216:217], v204 offset:16384
	ds_read_b64_tr_b16 v[218:219], v205 offset:16384
	ds_read_b64_tr_b16 v[228:229], v206 offset:16384
	ds_read_b64_tr_b16 v[230:231], v207 offset:16384
	ds_read_b64_tr_b16 v[238:239], v220 offset:20480
	ds_read_b64_tr_b16 v[240:241], v221 offset:20480
	ds_read_b64_tr_b16 v[242:243], v202 offset:20480
	ds_read_b64_tr_b16 v[244:245], v203 offset:20480
	ds_read_b64_tr_b16 v[246:247], v204 offset:20480
	ds_read_b64_tr_b16 v[248:249], v205 offset:20480
	ds_read_b64_tr_b16 v[250:251], v206 offset:20480
	ds_read_b64_tr_b16 v[252:253], v207 offset:20480
	v_max_f32_e32 v177, v64, v64
	v_max_f32_e32 v178, v80, v80
	v_max_f32_e32 v177, v178, v177
	v_max_f32_e32 v178, v81, v65
	v_max3_f32 v177, v177, v82, v66
	v_max3_f32 v178, v178, v83, v67
	v_max3_f32 v177, v177, v84, v68
	v_max3_f32 v178, v178, v85, v69
	v_max3_f32 v177, v177, v86, v70
	v_max3_f32 v178, v178, v87, v71
	v_max3_f32 v177, v177, v88, v72
	v_max3_f32 v178, v178, v89, v73
	v_max3_f32 v177, v177, v90, v74
	v_max3_f32 v178, v178, v91, v75
	v_max3_f32 v177, v177, v92, v76
	v_max3_f32 v178, v178, v93, v77
	v_max3_f32 v177, v177, v94, v78
	v_max3_f32 v178, v178, v95, v79
	v_max_f32_e32 v177, v177, v178
	v_max_f32_e32 v177, v177, v177
	v_mov_b32_e32 v178, v177
	s_nop 1
	v_permlane32_swap_b32_e32 v178, v177
	v_max_f32_e32 v177, v177, v178
	v_mul_f32_e32 v177, 0x3e0293ee, v177
	v_add_f32_e32 v178, 0x41000000, v176
	v_cmp_gt_f32_e32 vcc, v177, v178
	s_cbranch_vccz .LBB0_178
	s_nop 0
	v_cndmask_b32_e32 v177, v176, v177, vcc
	v_sub_f32_e32 v176, v176, v177
	v_exp_f32_e32 v176, v176
	s_nop 0
	v_pk_mul_f32 v[62:63], v[62:63], v[176:177] op_sel_hi:[1,0]
	v_pk_mul_f32 v[60:61], v[60:61], v[176:177] op_sel_hi:[1,0]
	v_pk_mul_f32 v[58:59], v[58:59], v[176:177] op_sel_hi:[1,0]
	v_pk_mul_f32 v[56:57], v[56:57], v[176:177] op_sel_hi:[1,0]
	v_pk_mul_f32 v[54:55], v[54:55], v[176:177] op_sel_hi:[1,0]
	v_pk_mul_f32 v[52:53], v[52:53], v[176:177] op_sel_hi:[1,0]
	v_pk_mul_f32 v[50:51], v[50:51], v[176:177] op_sel_hi:[1,0]
	v_pk_mul_f32 v[48:49], v[48:49], v[176:177] op_sel_hi:[1,0]
	v_pk_mul_f32 v[46:47], v[46:47], v[176:177] op_sel_hi:[1,0]
	v_pk_mul_f32 v[44:45], v[44:45], v[176:177] op_sel_hi:[1,0]
	v_pk_mul_f32 v[42:43], v[42:43], v[176:177] op_sel_hi:[1,0]
	v_pk_mul_f32 v[40:41], v[40:41], v[176:177] op_sel_hi:[1,0]
	v_pk_mul_f32 v[38:39], v[38:39], v[176:177] op_sel_hi:[1,0]
	v_pk_mul_f32 v[36:37], v[36:37], v[176:177] op_sel_hi:[1,0]
	v_pk_mul_f32 v[34:35], v[34:35], v[176:177] op_sel_hi:[1,0]
	v_pk_mul_f32 v[32:33], v[32:33], v[176:177] op_sel_hi:[1,0]
	v_pk_mul_f32 v[30:31], v[30:31], v[176:177] op_sel_hi:[1,0]
	v_pk_mul_f32 v[28:29], v[28:29], v[176:177] op_sel_hi:[1,0]
	v_pk_mul_f32 v[26:27], v[26:27], v[176:177] op_sel_hi:[1,0]
	v_pk_mul_f32 v[24:25], v[24:25], v[176:177] op_sel_hi:[1,0]
	v_pk_mul_f32 v[22:23], v[22:23], v[176:177] op_sel_hi:[1,0]
	v_pk_mul_f32 v[20:21], v[20:21], v[176:177] op_sel_hi:[1,0]
	v_pk_mul_f32 v[18:19], v[18:19], v[176:177] op_sel_hi:[1,0]
	v_pk_mul_f32 v[16:17], v[16:17], v[176:177] op_sel_hi:[1,0]
	v_pk_mul_f32 v[14:15], v[14:15], v[176:177] op_sel_hi:[1,0]
	v_pk_mul_f32 v[12:13], v[12:13], v[176:177] op_sel_hi:[1,0]
	v_pk_mul_f32 v[10:11], v[10:11], v[176:177] op_sel_hi:[1,0]
	v_pk_mul_f32 v[8:9], v[8:9], v[176:177] op_sel_hi:[1,0]
	v_pk_mul_f32 v[6:7], v[6:7], v[176:177] op_sel_hi:[1,0]
	v_pk_mul_f32 v[4:5], v[4:5], v[176:177] op_sel_hi:[1,0]
	v_pk_mul_f32 v[2:3], v[2:3], v[176:177] op_sel_hi:[1,0]
	v_pk_mul_f32 v[0:1], v[0:1], v[176:177] op_sel_hi:[1,0]
	v_mul_f32_e32 v173, v173, v176
	v_mov_b32_e32 v176, v177
